# scan inner loop: 2 rows x 4 columns per lane with butterfly-only 16-lane DPP reductions (row_ror:8 transposing step) so all lanes of a row hold bitwise identical sums; fixes run-to-run variation of th
# speedup vs baseline: 1.0038x; 1.0038x over previous
.LBB0_642:
	s_or_b64 exec, exec, s[6:7]
	s_and_b32 s12, s22, 1
	s_and_b64 s[6:7], s[50:51], exec
	s_mov_b32 s1, 0x1a160000
	s_cselect_b32 s6, s1, 0x1b360000
	s_add_u32 s6, s94, s6
	s_addc_u32 s7, s95, 0
	s_lshl_b32 s13, s12, 5
	v_lshlrev_b32_e32 v158, 3, v81
	v_lshrrev_b32_e32 v79, 3, v79
	v_lshl_add_u32 v83, v87, 3, s13
	v_or_b32_e32 v179, v83, v79
	v_lshlrev_b32_e32 v79, 2, v158
	v_readlane_b32 s13, v252, 11
	v_lshl_add_u32 v83, v178, 8, 0
	v_lshlrev_b32_e32 v84, 1, v158
	v_add_u32_e32 v180, s13, v79
	v_readlane_b32 s13, v252, 12
	v_lshl_add_u32 v188, v179, 2, 0
	v_mov_b32_e32 v159, v0
	v_add_u32_e32 v182, s13, v79
	v_readlane_b32 s13, v252, 13
	v_cmp_eq_u32_e64 s[42:43], 0, v81
	v_or_b32_e32 v81, s12, v81
	v_add_u32_e32 v183, s13, v79
	v_readlane_b32 s13, v252, 14
	v_bfe_u32 v1, v80, 4, 2
	v_cmp_eq_u32_e64 s[44:45], 0, v81
	v_add_u32_e32 v184, s13, v79
	v_readlane_b32 s13, v252, 23
	v_lshlrev_b32_e32 v80, 3, v1
	v_add_u32_e32 v181, v83, v79
	v_add_u32_e32 v185, s13, v79
	s_movk_i32 s13, 0xff90
	v_mul_lo_u32 v85, v178, s13
	v_readlane_b32 s13, v253, 18
	v_add3_u32 v186, v83, v85, v84
	v_mov_b32_e32 v85, v0
	v_add_u32_e32 v187, s13, v79
	s_add_u32 s13, s6, s52
	s_addc_u32 s14, s7, 0
	s_and_b64 s[6:7], s[50:51], exec
	s_cselect_b32 s6, 0, 0x7c0
	v_lshl_add_u64 v[160:161], s[80:81], 0, v[84:85]
	v_or_b32_e32 v84, s6, v158
	v_lshl_add_u32 v190, s6, 2, v188
	s_lshl_b32 s6, s12, 7
	v_add3_u32 v191, v83, s6, v82
	s_lshl_b32 s6, s12, 6
	s_add_u32 s6, s13, s6
	s_addc_u32 s7, s14, 0
	v_lshl_add_u64 v[162:163], s[6:7], 0, v[158:159]
	s_movk_i32 s6, 0xff04
	v_mul_lo_u32 v81, v178, s6
	s_lshl_b32 s6, s11, 3
	v_readlane_b32 s12, v252, 5
	v_readlane_b32 s13, v252, 6
	s_add_u32 s6, s12, s6
	v_lshlrev_b32_e32 v79, 1, v80
	v_lshlrev_b32_e32 v80, 7, v87
	s_addc_u32 s7, s13, 0
	s_lshl_b32 s10, s10, 2
	v_mul_u32_u24_e32 v82, 0x48, v86
	v_lshl_add_u32 v78, v1, 8, v78
	v_lshlrev_b32_e32 v1, 4, v1
	s_add_u32 s54, s6, s10
	v_lshlrev_b32_e32 v82, 1, v82
	v_lshl_add_u32 v193, v78, 2, 0
	v_add3_u32 v194, 0, v80, v1
	v_mov_b32_e32 v1, v0
	s_mov_b32 s1, 0
	v_cmp_eq_u32_e64 s[40:41], 0, v86
	v_lshl_add_u32 v189, v84, 2, 0
	v_and_b32_e32 v212, 63, v234
	v_and_b32_e32 v213, 0xffffff00, v189
	v_and_b32_e32 v214, 15, v212
	v_lshl_or_b32 v189, v214, 4, v213
	v_and_b32_e32 v214, 0xffffffe0, v188
	v_lshrrev_b32_e32 v215, 4, v212
	v_bfe_u32 v212, v212, 3, 1
	v_lshl_add_u32 v214, v215, 3, v214
	v_lshl_add_u32 v214, v212, 2, v214
	v_add_u32_e32 v190, v213, v214
	v_xor_b32_e32 v210, 4, v190
	v_add_u32_e32 v192, s79, v178
	s_addc_u32 s55, s7, 0
	v_add3_u32 v159, 0, v79, v82
	v_add_u32_e32 v195, 0x100, v193
	v_add_u32_e32 v196, 0x200, v193
	v_add_u32_e32 v197, 0x300, v193
	v_add_u32_e32 v198, 0x1000, v193
	v_add_u32_e32 v199, 0x1100, v193
	v_add_u32_e32 v200, 0x1200, v193
	v_add_u32_e32 v201, 0x1300, v193
	v_add_u32_e32 v202, v83, v81
	v_mov_b64_e32 v[164:165], v[0:1]
	v_mov_b64_e32 v[166:167], v[0:1]
	v_mov_b64_e32 v[168:169], v[0:1]
	v_mov_b64_e32 v[170:171], v[0:1]
	s_waitcnt vmcnt(0) lgkmcnt(0)
	s_barrier
	s_branch .LBB0_644

.LBB0_682:
	s_waitcnt lgkmcnt(0)
	s_barrier
	ds_read_b128 v[78:81], v189 offset:16384
	ds_read_b128 v[82:85], v189 offset:40960
	ds_read_b128 v[86:89], v189 offset:24576
	ds_read_b128 v[90:93], v189 offset:32768
	ds_read_b128 v[94:97], v189
	ds_read_b32 v98, v190 offset:8192
	ds_read_b32 v99, v210 offset:8192
	s_and_b64 vcc, exec, s[50:51]
	s_cbranch_vccz .Lscan_rev
	s_movk_i32 s12, 0x400
	v_mov_b32_e32 v207, v189
	v_mov_b32_e32 v208, v190
	v_mov_b32_e32 v209, v190
	v_mov_b32_e32 v211, v210
	s_waitcnt lgkmcnt(0)
	ds_read_b128 v[118:121], v207 offset:16640
	ds_read_b128 v[122:125], v207 offset:41216
	ds_read_b128 v[126:129], v207 offset:24832
	ds_read_b128 v[130:133], v207 offset:33024
	ds_read_b128 v[134:137], v207 offset:256
	ds_read_b32 v138, v208 offset:8448
	ds_read_b32 v139, v211 offset:8448
	v_pk_mul_f32 v[212:213], v[164:165], v[78:79] op_sel_hi:[1,0]
	v_pk_fma_f32 v[212:213], v[166:167], v[78:79], v[212:213] op_sel:[0,1,0] op_sel_hi:[1,1,1]
	v_pk_fma_f32 v[212:213], v[168:169], v[80:81], v[212:213] op_sel_hi:[1,0,1]
	v_pk_fma_f32 v[212:213], v[170:171], v[80:81], v[212:213] op_sel:[0,1,0] op_sel_hi:[1,1,1]
	v_pk_mul_f32 v[164:165], v[90:91], v[164:165] op_sel_hi:[0,1]
	v_pk_mul_f32 v[166:167], v[90:91], v[166:167] op_sel:[1,0] op_sel_hi:[1,1]
	v_add_f32_dpp v220, v213, v212 row_ror:8 row_mask:0xf bank_mask:0xf
	v_pk_mul_f32 v[168:169], v[92:93], v[168:169] op_sel_hi:[0,1]
	v_pk_mul_f32 v[170:171], v[92:93], v[170:171] op_sel:[1,0] op_sel_hi:[1,1]
	v_add_f32_dpp v220, v220, v220 quad_perm:[1,0,3,2] row_mask:0xf bank_mask:0xf
	v_pk_fma_f32 v[164:165], v[86:87], v[98:99], v[164:165] op_sel_hi:[0,1,1]
	v_pk_fma_f32 v[166:167], v[86:87], v[98:99], v[166:167] op_sel:[1,0,0] op_sel_hi:[1,1,1]
	v_add_f32_dpp v220, v220, v220 quad_perm:[2,3,0,1] row_mask:0xf bank_mask:0xf
	v_pk_fma_f32 v[168:169], v[88:89], v[98:99], v[168:169] op_sel_hi:[0,1,1]
	v_pk_fma_f32 v[170:171], v[88:89], v[98:99], v[170:171] op_sel:[1,0,0] op_sel_hi:[1,1,1]
	v_add_f32_dpp v220, v220, v220 row_half_mirror row_mask:0xf bank_mask:0xf
	s_nop 1
	v_mov_b32_dpp v221, v220 row_ror:8 row_mask:0xf bank_mask:0xf
	v_pk_fma_f32 v[164:165], v[82:83], v[220:221], v[164:165] op_sel_hi:[0,1,1] neg_lo:[0,1,0] neg_hi:[0,1,0]
	v_pk_fma_f32 v[166:167], v[82:83], v[220:221], v[166:167] op_sel:[1,0,0] op_sel_hi:[1,1,1] neg_lo:[0,1,0] neg_hi:[0,1,0]
	v_pk_fma_f32 v[168:169], v[84:85], v[220:221], v[168:169] op_sel_hi:[0,1,1] neg_lo:[0,1,0] neg_hi:[0,1,0]
	v_pk_fma_f32 v[170:171], v[84:85], v[220:221], v[170:171] op_sel:[1,0,0] op_sel_hi:[1,1,1] neg_lo:[0,1,0] neg_hi:[0,1,0]
	v_pk_mul_f32 v[216:217], v[164:165], v[94:95] op_sel_hi:[1,0]
	v_pk_fma_f32 v[216:217], v[166:167], v[94:95], v[216:217] op_sel:[0,1,0] op_sel_hi:[1,1,1]
	v_pk_fma_f32 v[216:217], v[168:169], v[96:97], v[216:217] op_sel_hi:[1,0,1]
	v_pk_fma_f32 v[216:217], v[170:171], v[96:97], v[216:217] op_sel:[0,1,0] op_sel_hi:[1,1,1]
	s_waitcnt lgkmcnt(0)
	ds_read_b128 v[78:81], v207 offset:16896
	ds_read_b128 v[82:85], v207 offset:41472
	ds_read_b128 v[86:89], v207 offset:25088
	ds_read_b128 v[90:93], v207 offset:33280
	ds_read_b128 v[94:97], v207 offset:512
	ds_read_b32 v98, v208 offset:8704
	ds_read_b32 v99, v211 offset:8704
	v_pk_mul_f32 v[212:213], v[164:165], v[118:119] op_sel_hi:[1,0]
	v_pk_fma_f32 v[212:213], v[166:167], v[118:119], v[212:213] op_sel:[0,1,0] op_sel_hi:[1,1,1]
	v_add_f32_dpp v224, v217, v216 row_ror:8 row_mask:0xf bank_mask:0xf
	v_pk_fma_f32 v[212:213], v[168:169], v[120:121], v[212:213] op_sel_hi:[1,0,1]
	v_pk_fma_f32 v[212:213], v[170:171], v[120:121], v[212:213] op_sel:[0,1,0] op_sel_hi:[1,1,1]
	v_add_f32_dpp v224, v224, v224 quad_perm:[1,0,3,2] row_mask:0xf bank_mask:0xf
	v_pk_mul_f32 v[164:165], v[130:131], v[164:165] op_sel_hi:[0,1]
	v_pk_mul_f32 v[166:167], v[130:131], v[166:167] op_sel:[1,0] op_sel_hi:[1,1]
	v_add_f32_dpp v220, v213, v212 row_ror:8 row_mask:0xf bank_mask:0xf
	v_add_f32_dpp v224, v224, v224 quad_perm:[2,3,0,1] row_mask:0xf bank_mask:0xf
	v_pk_mul_f32 v[168:169], v[132:133], v[168:169] op_sel_hi:[0,1]
	v_add_f32_dpp v220, v220, v220 quad_perm:[1,0,3,2] row_mask:0xf bank_mask:0xf
	v_add_f32_dpp v224, v224, v224 row_half_mirror row_mask:0xf bank_mask:0xf
	v_pk_mul_f32 v[170:171], v[132:133], v[170:171] op_sel:[1,0] op_sel_hi:[1,1]
	v_pk_fma_f32 v[164:165], v[126:127], v[138:139], v[164:165] op_sel_hi:[0,1,1]
	v_add_f32_dpp v220, v220, v220 quad_perm:[2,3,0,1] row_mask:0xf bank_mask:0xf
	ds_write_b32 v209, v224 offset:49152
	v_pk_fma_f32 v[166:167], v[126:127], v[138:139], v[166:167] op_sel:[1,0,0] op_sel_hi:[1,1,1]
	v_pk_fma_f32 v[168:169], v[128:129], v[138:139], v[168:169] op_sel_hi:[0,1,1]
	v_add_f32_dpp v220, v220, v220 row_half_mirror row_mask:0xf bank_mask:0xf
	v_pk_fma_f32 v[170:171], v[128:129], v[138:139], v[170:171] op_sel:[1,0,0] op_sel_hi:[1,1,1]
	s_nop 0
	v_mov_b32_dpp v221, v220 row_ror:8 row_mask:0xf bank_mask:0xf
	v_pk_fma_f32 v[164:165], v[122:123], v[220:221], v[164:165] op_sel_hi:[0,1,1] neg_lo:[0,1,0] neg_hi:[0,1,0]
	v_pk_fma_f32 v[166:167], v[122:123], v[220:221], v[166:167] op_sel:[1,0,0] op_sel_hi:[1,1,1] neg_lo:[0,1,0] neg_hi:[0,1,0]
	v_pk_fma_f32 v[168:169], v[124:125], v[220:221], v[168:169] op_sel_hi:[0,1,1] neg_lo:[0,1,0] neg_hi:[0,1,0]
	v_pk_fma_f32 v[170:171], v[124:125], v[220:221], v[170:171] op_sel:[1,0,0] op_sel_hi:[1,1,1] neg_lo:[0,1,0] neg_hi:[0,1,0]
	v_pk_mul_f32 v[216:217], v[164:165], v[134:135] op_sel_hi:[1,0]
	v_pk_fma_f32 v[216:217], v[166:167], v[134:135], v[216:217] op_sel:[0,1,0] op_sel_hi:[1,1,1]
	v_pk_fma_f32 v[216:217], v[168:169], v[136:137], v[216:217] op_sel_hi:[1,0,1]
	v_pk_fma_f32 v[216:217], v[170:171], v[136:137], v[216:217] op_sel:[0,1,0] op_sel_hi:[1,1,1]
	s_waitcnt lgkmcnt(0)
	ds_read_b128 v[118:121], v207 offset:17152
	ds_read_b128 v[122:125], v207 offset:41728
	ds_read_b128 v[126:129], v207 offset:25344
	ds_read_b128 v[130:133], v207 offset:33536
	ds_read_b128 v[134:137], v207 offset:768
	ds_read_b32 v138, v208 offset:8960
	ds_read_b32 v139, v211 offset:8960
	v_pk_mul_f32 v[212:213], v[164:165], v[78:79] op_sel_hi:[1,0]
	v_pk_fma_f32 v[212:213], v[166:167], v[78:79], v[212:213] op_sel:[0,1,0] op_sel_hi:[1,1,1]
	v_add_f32_dpp v224, v217, v216 row_ror:8 row_mask:0xf bank_mask:0xf
	v_pk_fma_f32 v[212:213], v[168:169], v[80:81], v[212:213] op_sel_hi:[1,0,1]
	v_pk_fma_f32 v[212:213], v[170:171], v[80:81], v[212:213] op_sel:[0,1,0] op_sel_hi:[1,1,1]
	v_add_f32_dpp v224, v224, v224 quad_perm:[1,0,3,2] row_mask:0xf bank_mask:0xf
	v_pk_mul_f32 v[164:165], v[90:91], v[164:165] op_sel_hi:[0,1]
	v_pk_mul_f32 v[166:167], v[90:91], v[166:167] op_sel:[1,0] op_sel_hi:[1,1]
	v_add_f32_dpp v220, v213, v212 row_ror:8 row_mask:0xf bank_mask:0xf
	v_add_f32_dpp v224, v224, v224 quad_perm:[2,3,0,1] row_mask:0xf bank_mask:0xf
	v_pk_mul_f32 v[168:169], v[92:93], v[168:169] op_sel_hi:[0,1]
	v_add_f32_dpp v220, v220, v220 quad_perm:[1,0,3,2] row_mask:0xf bank_mask:0xf
	v_add_f32_dpp v224, v224, v224 row_half_mirror row_mask:0xf bank_mask:0xf
	v_pk_mul_f32 v[170:171], v[92:93], v[170:171] op_sel:[1,0] op_sel_hi:[1,1]
	v_pk_fma_f32 v[164:165], v[86:87], v[98:99], v[164:165] op_sel_hi:[0,1,1]
	v_add_f32_dpp v220, v220, v220 quad_perm:[2,3,0,1] row_mask:0xf bank_mask:0xf
	ds_write_b32 v209, v224 offset:49408
	v_pk_fma_f32 v[166:167], v[86:87], v[98:99], v[166:167] op_sel:[1,0,0] op_sel_hi:[1,1,1]
	v_pk_fma_f32 v[168:169], v[88:89], v[98:99], v[168:169] op_sel_hi:[0,1,1]
	v_add_f32_dpp v220, v220, v220 row_half_mirror row_mask:0xf bank_mask:0xf
	v_pk_fma_f32 v[170:171], v[88:89], v[98:99], v[170:171] op_sel:[1,0,0] op_sel_hi:[1,1,1]
	s_nop 0
	v_mov_b32_dpp v221, v220 row_ror:8 row_mask:0xf bank_mask:0xf
	v_pk_fma_f32 v[164:165], v[82:83], v[220:221], v[164:165] op_sel_hi:[0,1,1] neg_lo:[0,1,0] neg_hi:[0,1,0]
	v_pk_fma_f32 v[166:167], v[82:83], v[220:221], v[166:167] op_sel:[1,0,0] op_sel_hi:[1,1,1] neg_lo:[0,1,0] neg_hi:[0,1,0]
	v_pk_fma_f32 v[168:169], v[84:85], v[220:221], v[168:169] op_sel_hi:[0,1,1] neg_lo:[0,1,0] neg_hi:[0,1,0]
	v_pk_fma_f32 v[170:171], v[84:85], v[220:221], v[170:171] op_sel:[1,0,0] op_sel_hi:[1,1,1] neg_lo:[0,1,0] neg_hi:[0,1,0]
	v_pk_mul_f32 v[216:217], v[164:165], v[94:95] op_sel_hi:[1,0]
	v_pk_fma_f32 v[216:217], v[166:167], v[94:95], v[216:217] op_sel:[0,1,0] op_sel_hi:[1,1,1]
	v_pk_fma_f32 v[216:217], v[168:169], v[96:97], v[216:217] op_sel_hi:[1,0,1]
	v_pk_fma_f32 v[216:217], v[170:171], v[96:97], v[216:217] op_sel:[0,1,0] op_sel_hi:[1,1,1]
	s_waitcnt lgkmcnt(0)
	v_add_u32_e32 v207, s12, v207
	v_add_u32_e32 v208, s12, v208
	v_add_u32_e32 v211, s12, v211
	ds_read_b128 v[78:81], v207 offset:16384
	ds_read_b128 v[82:85], v207 offset:40960
	ds_read_b128 v[86:89], v207 offset:24576
	ds_read_b128 v[90:93], v207 offset:32768
	ds_read_b128 v[94:97], v207 offset:0
	ds_read_b32 v98, v208 offset:8192
	ds_read_b32 v99, v211 offset:8192
	v_pk_mul_f32 v[212:213], v[164:165], v[118:119] op_sel_hi:[1,0]
	v_pk_fma_f32 v[212:213], v[166:167], v[118:119], v[212:213] op_sel:[0,1,0] op_sel_hi:[1,1,1]
	v_add_f32_dpp v224, v217, v216 row_ror:8 row_mask:0xf bank_mask:0xf
	v_pk_fma_f32 v[212:213], v[168:169], v[120:121], v[212:213] op_sel_hi:[1,0,1]
	v_pk_fma_f32 v[212:213], v[170:171], v[120:121], v[212:213] op_sel:[0,1,0] op_sel_hi:[1,1,1]
	v_add_f32_dpp v224, v224, v224 quad_perm:[1,0,3,2] row_mask:0xf bank_mask:0xf
	v_pk_mul_f32 v[164:165], v[130:131], v[164:165] op_sel_hi:[0,1]
	v_pk_mul_f32 v[166:167], v[130:131], v[166:167] op_sel:[1,0] op_sel_hi:[1,1]
	v_add_f32_dpp v220, v213, v212 row_ror:8 row_mask:0xf bank_mask:0xf
	v_add_f32_dpp v224, v224, v224 quad_perm:[2,3,0,1] row_mask:0xf bank_mask:0xf
	v_pk_mul_f32 v[168:169], v[132:133], v[168:169] op_sel_hi:[0,1]
	v_add_f32_dpp v220, v220, v220 quad_perm:[1,0,3,2] row_mask:0xf bank_mask:0xf
	v_add_f32_dpp v224, v224, v224 row_half_mirror row_mask:0xf bank_mask:0xf
	v_pk_mul_f32 v[170:171], v[132:133], v[170:171] op_sel:[1,0] op_sel_hi:[1,1]
	v_pk_fma_f32 v[164:165], v[126:127], v[138:139], v[164:165] op_sel_hi:[0,1,1]
	v_add_f32_dpp v220, v220, v220 quad_perm:[2,3,0,1] row_mask:0xf bank_mask:0xf
	ds_write_b32 v209, v224 offset:49664
	v_pk_fma_f32 v[166:167], v[126:127], v[138:139], v[166:167] op_sel:[1,0,0] op_sel_hi:[1,1,1]
	v_pk_fma_f32 v[168:169], v[128:129], v[138:139], v[168:169] op_sel_hi:[0,1,1]
	v_add_f32_dpp v220, v220, v220 row_half_mirror row_mask:0xf bank_mask:0xf
	v_pk_fma_f32 v[170:171], v[128:129], v[138:139], v[170:171] op_sel:[1,0,0] op_sel_hi:[1,1,1]
	s_nop 0
	v_mov_b32_dpp v221, v220 row_ror:8 row_mask:0xf bank_mask:0xf
	v_pk_fma_f32 v[164:165], v[122:123], v[220:221], v[164:165] op_sel_hi:[0,1,1] neg_lo:[0,1,0] neg_hi:[0,1,0]
	v_pk_fma_f32 v[166:167], v[122:123], v[220:221], v[166:167] op_sel:[1,0,0] op_sel_hi:[1,1,1] neg_lo:[0,1,0] neg_hi:[0,1,0]
	v_pk_fma_f32 v[168:169], v[124:125], v[220:221], v[168:169] op_sel_hi:[0,1,1] neg_lo:[0,1,0] neg_hi:[0,1,0]
	v_pk_fma_f32 v[170:171], v[124:125], v[220:221], v[170:171] op_sel:[1,0,0] op_sel_hi:[1,1,1] neg_lo:[0,1,0] neg_hi:[0,1,0]
	v_pk_mul_f32 v[216:217], v[164:165], v[134:135] op_sel_hi:[1,0]
	v_pk_fma_f32 v[216:217], v[166:167], v[134:135], v[216:217] op_sel:[0,1,0] op_sel_hi:[1,1,1]
	v_pk_fma_f32 v[216:217], v[168:169], v[136:137], v[216:217] op_sel_hi:[1,0,1]
	v_pk_fma_f32 v[216:217], v[170:171], v[136:137], v[216:217] op_sel:[0,1,0] op_sel_hi:[1,1,1]
	s_mov_b32 s11, 1
.Lscan_fwd_loop:
	s_waitcnt lgkmcnt(0)
	ds_read_b128 v[118:121], v207 offset:16640
	ds_read_b128 v[122:125], v207 offset:41216
	ds_read_b128 v[126:129], v207 offset:24832
	ds_read_b128 v[130:133], v207 offset:33024
	ds_read_b128 v[134:137], v207 offset:256
	ds_read_b32 v138, v208 offset:8448
	ds_read_b32 v139, v211 offset:8448
	v_pk_mul_f32 v[212:213], v[164:165], v[78:79] op_sel_hi:[1,0]
	v_pk_fma_f32 v[212:213], v[166:167], v[78:79], v[212:213] op_sel:[0,1,0] op_sel_hi:[1,1,1]
	v_add_f32_dpp v224, v217, v216 row_ror:8 row_mask:0xf bank_mask:0xf
	v_pk_fma_f32 v[212:213], v[168:169], v[80:81], v[212:213] op_sel_hi:[1,0,1]
	v_pk_fma_f32 v[212:213], v[170:171], v[80:81], v[212:213] op_sel:[0,1,0] op_sel_hi:[1,1,1]
	v_add_f32_dpp v224, v224, v224 quad_perm:[1,0,3,2] row_mask:0xf bank_mask:0xf
	v_pk_mul_f32 v[164:165], v[90:91], v[164:165] op_sel_hi:[0,1]
	v_pk_mul_f32 v[166:167], v[90:91], v[166:167] op_sel:[1,0] op_sel_hi:[1,1]
	v_add_f32_dpp v220, v213, v212 row_ror:8 row_mask:0xf bank_mask:0xf
	v_add_f32_dpp v224, v224, v224 quad_perm:[2,3,0,1] row_mask:0xf bank_mask:0xf
	v_pk_mul_f32 v[168:169], v[92:93], v[168:169] op_sel_hi:[0,1]
	v_add_f32_dpp v220, v220, v220 quad_perm:[1,0,3,2] row_mask:0xf bank_mask:0xf
	v_add_f32_dpp v224, v224, v224 row_half_mirror row_mask:0xf bank_mask:0xf
	v_pk_mul_f32 v[170:171], v[92:93], v[170:171] op_sel:[1,0] op_sel_hi:[1,1]
	v_pk_fma_f32 v[164:165], v[86:87], v[98:99], v[164:165] op_sel_hi:[0,1,1]
	v_add_f32_dpp v220, v220, v220 quad_perm:[2,3,0,1] row_mask:0xf bank_mask:0xf
	ds_write_b32 v209, v224 offset:49920
	v_add_u32_e32 v209, s12, v209
	v_pk_fma_f32 v[166:167], v[86:87], v[98:99], v[166:167] op_sel:[1,0,0] op_sel_hi:[1,1,1]
	v_pk_fma_f32 v[168:169], v[88:89], v[98:99], v[168:169] op_sel_hi:[0,1,1]
	v_add_f32_dpp v220, v220, v220 row_half_mirror row_mask:0xf bank_mask:0xf
	v_pk_fma_f32 v[170:171], v[88:89], v[98:99], v[170:171] op_sel:[1,0,0] op_sel_hi:[1,1,1]
	s_nop 0
	v_mov_b32_dpp v221, v220 row_ror:8 row_mask:0xf bank_mask:0xf
	v_pk_fma_f32 v[164:165], v[82:83], v[220:221], v[164:165] op_sel_hi:[0,1,1] neg_lo:[0,1,0] neg_hi:[0,1,0]
	v_pk_fma_f32 v[166:167], v[82:83], v[220:221], v[166:167] op_sel:[1,0,0] op_sel_hi:[1,1,1] neg_lo:[0,1,0] neg_hi:[0,1,0]
	v_pk_fma_f32 v[168:169], v[84:85], v[220:221], v[168:169] op_sel_hi:[0,1,1] neg_lo:[0,1,0] neg_hi:[0,1,0]
	v_pk_fma_f32 v[170:171], v[84:85], v[220:221], v[170:171] op_sel:[1,0,0] op_sel_hi:[1,1,1] neg_lo:[0,1,0] neg_hi:[0,1,0]
	v_pk_mul_f32 v[216:217], v[164:165], v[94:95] op_sel_hi:[1,0]
	v_pk_fma_f32 v[216:217], v[166:167], v[94:95], v[216:217] op_sel:[0,1,0] op_sel_hi:[1,1,1]
	v_pk_fma_f32 v[216:217], v[168:169], v[96:97], v[216:217] op_sel_hi:[1,0,1]
	v_pk_fma_f32 v[216:217], v[170:171], v[96:97], v[216:217] op_sel:[0,1,0] op_sel_hi:[1,1,1]
	s_waitcnt lgkmcnt(0)
	ds_read_b128 v[78:81], v207 offset:16896
	ds_read_b128 v[82:85], v207 offset:41472
	ds_read_b128 v[86:89], v207 offset:25088
	ds_read_b128 v[90:93], v207 offset:33280
	ds_read_b128 v[94:97], v207 offset:512
	ds_read_b32 v98, v208 offset:8704
	ds_read_b32 v99, v211 offset:8704
	v_pk_mul_f32 v[212:213], v[164:165], v[118:119] op_sel_hi:[1,0]
	v_pk_fma_f32 v[212:213], v[166:167], v[118:119], v[212:213] op_sel:[0,1,0] op_sel_hi:[1,1,1]
	v_add_f32_dpp v224, v217, v216 row_ror:8 row_mask:0xf bank_mask:0xf
	v_pk_fma_f32 v[212:213], v[168:169], v[120:121], v[212:213] op_sel_hi:[1,0,1]
	v_pk_fma_f32 v[212:213], v[170:171], v[120:121], v[212:213] op_sel:[0,1,0] op_sel_hi:[1,1,1]
	v_add_f32_dpp v224, v224, v224 quad_perm:[1,0,3,2] row_mask:0xf bank_mask:0xf
	v_pk_mul_f32 v[164:165], v[130:131], v[164:165] op_sel_hi:[0,1]
	v_pk_mul_f32 v[166:167], v[130:131], v[166:167] op_sel:[1,0] op_sel_hi:[1,1]
	v_add_f32_dpp v220, v213, v212 row_ror:8 row_mask:0xf bank_mask:0xf
	v_add_f32_dpp v224, v224, v224 quad_perm:[2,3,0,1] row_mask:0xf bank_mask:0xf
	v_pk_mul_f32 v[168:169], v[132:133], v[168:169] op_sel_hi:[0,1]
	v_add_f32_dpp v220, v220, v220 quad_perm:[1,0,3,2] row_mask:0xf bank_mask:0xf
	v_add_f32_dpp v224, v224, v224 row_half_mirror row_mask:0xf bank_mask:0xf
	v_pk_mul_f32 v[170:171], v[132:133], v[170:171] op_sel:[1,0] op_sel_hi:[1,1]
	v_pk_fma_f32 v[164:165], v[126:127], v[138:139], v[164:165] op_sel_hi:[0,1,1]
	v_add_f32_dpp v220, v220, v220 quad_perm:[2,3,0,1] row_mask:0xf bank_mask:0xf
	ds_write_b32 v209, v224 offset:49152
	v_pk_fma_f32 v[166:167], v[126:127], v[138:139], v[166:167] op_sel:[1,0,0] op_sel_hi:[1,1,1]
	v_pk_fma_f32 v[168:169], v[128:129], v[138:139], v[168:169] op_sel_hi:[0,1,1]
	v_add_f32_dpp v220, v220, v220 row_half_mirror row_mask:0xf bank_mask:0xf
	v_pk_fma_f32 v[170:171], v[128:129], v[138:139], v[170:171] op_sel:[1,0,0] op_sel_hi:[1,1,1]
	s_nop 0
	v_mov_b32_dpp v221, v220 row_ror:8 row_mask:0xf bank_mask:0xf
	v_pk_fma_f32 v[164:165], v[122:123], v[220:221], v[164:165] op_sel_hi:[0,1,1] neg_lo:[0,1,0] neg_hi:[0,1,0]
	v_pk_fma_f32 v[166:167], v[122:123], v[220:221], v[166:167] op_sel:[1,0,0] op_sel_hi:[1,1,1] neg_lo:[0,1,0] neg_hi:[0,1,0]
	v_pk_fma_f32 v[168:169], v[124:125], v[220:221], v[168:169] op_sel_hi:[0,1,1] neg_lo:[0,1,0] neg_hi:[0,1,0]
	v_pk_fma_f32 v[170:171], v[124:125], v[220:221], v[170:171] op_sel:[1,0,0] op_sel_hi:[1,1,1] neg_lo:[0,1,0] neg_hi:[0,1,0]
	v_pk_mul_f32 v[216:217], v[164:165], v[134:135] op_sel_hi:[1,0]
	v_pk_fma_f32 v[216:217], v[166:167], v[134:135], v[216:217] op_sel:[0,1,0] op_sel_hi:[1,1,1]
	v_pk_fma_f32 v[216:217], v[168:169], v[136:137], v[216:217] op_sel_hi:[1,0,1]
	v_pk_fma_f32 v[216:217], v[170:171], v[136:137], v[216:217] op_sel:[0,1,0] op_sel_hi:[1,1,1]
	s_waitcnt lgkmcnt(0)
	ds_read_b128 v[118:121], v207 offset:17152
	ds_read_b128 v[122:125], v207 offset:41728
	ds_read_b128 v[126:129], v207 offset:25344
	ds_read_b128 v[130:133], v207 offset:33536
	ds_read_b128 v[134:137], v207 offset:768
	ds_read_b32 v138, v208 offset:8960
	ds_read_b32 v139, v211 offset:8960
	v_pk_mul_f32 v[212:213], v[164:165], v[78:79] op_sel_hi:[1,0]
	v_pk_fma_f32 v[212:213], v[166:167], v[78:79], v[212:213] op_sel:[0,1,0] op_sel_hi:[1,1,1]
	v_add_f32_dpp v224, v217, v216 row_ror:8 row_mask:0xf bank_mask:0xf
	v_pk_fma_f32 v[212:213], v[168:169], v[80:81], v[212:213] op_sel_hi:[1,0,1]
	v_pk_fma_f32 v[212:213], v[170:171], v[80:81], v[212:213] op_sel:[0,1,0] op_sel_hi:[1,1,1]
	v_add_f32_dpp v224, v224, v224 quad_perm:[1,0,3,2] row_mask:0xf bank_mask:0xf
	v_pk_mul_f32 v[164:165], v[90:91], v[164:165] op_sel_hi:[0,1]
	v_pk_mul_f32 v[166:167], v[90:91], v[166:167] op_sel:[1,0] op_sel_hi:[1,1]
	v_add_f32_dpp v220, v213, v212 row_ror:8 row_mask:0xf bank_mask:0xf
	v_add_f32_dpp v224, v224, v224 quad_perm:[2,3,0,1] row_mask:0xf bank_mask:0xf
	v_pk_mul_f32 v[168:169], v[92:93], v[168:169] op_sel_hi:[0,1]
	v_add_f32_dpp v220, v220, v220 quad_perm:[1,0,3,2] row_mask:0xf bank_mask:0xf
	v_add_f32_dpp v224, v224, v224 row_half_mirror row_mask:0xf bank_mask:0xf
	v_pk_mul_f32 v[170:171], v[92:93], v[170:171] op_sel:[1,0] op_sel_hi:[1,1]
	v_pk_fma_f32 v[164:165], v[86:87], v[98:99], v[164:165] op_sel_hi:[0,1,1]
	v_add_f32_dpp v220, v220, v220 quad_perm:[2,3,0,1] row_mask:0xf bank_mask:0xf
	ds_write_b32 v209, v224 offset:49408
	v_pk_fma_f32 v[166:167], v[86:87], v[98:99], v[166:167] op_sel:[1,0,0] op_sel_hi:[1,1,1]
	v_pk_fma_f32 v[168:169], v[88:89], v[98:99], v[168:169] op_sel_hi:[0,1,1]
	v_add_f32_dpp v220, v220, v220 row_half_mirror row_mask:0xf bank_mask:0xf
	v_pk_fma_f32 v[170:171], v[88:89], v[98:99], v[170:171] op_sel:[1,0,0] op_sel_hi:[1,1,1]
	s_nop 0
	v_mov_b32_dpp v221, v220 row_ror:8 row_mask:0xf bank_mask:0xf
	v_pk_fma_f32 v[164:165], v[82:83], v[220:221], v[164:165] op_sel_hi:[0,1,1] neg_lo:[0,1,0] neg_hi:[0,1,0]
	v_pk_fma_f32 v[166:167], v[82:83], v[220:221], v[166:167] op_sel:[1,0,0] op_sel_hi:[1,1,1] neg_lo:[0,1,0] neg_hi:[0,1,0]
	v_pk_fma_f32 v[168:169], v[84:85], v[220:221], v[168:169] op_sel_hi:[0,1,1] neg_lo:[0,1,0] neg_hi:[0,1,0]
	v_pk_fma_f32 v[170:171], v[84:85], v[220:221], v[170:171] op_sel:[1,0,0] op_sel_hi:[1,1,1] neg_lo:[0,1,0] neg_hi:[0,1,0]
	v_pk_mul_f32 v[216:217], v[164:165], v[94:95] op_sel_hi:[1,0]
	v_pk_fma_f32 v[216:217], v[166:167], v[94:95], v[216:217] op_sel:[0,1,0] op_sel_hi:[1,1,1]
	v_pk_fma_f32 v[216:217], v[168:169], v[96:97], v[216:217] op_sel_hi:[1,0,1]
	v_pk_fma_f32 v[216:217], v[170:171], v[96:97], v[216:217] op_sel:[0,1,0] op_sel_hi:[1,1,1]
	s_waitcnt lgkmcnt(0)
	s_cmp_eq_u32 s11, 7
	s_cbranch_scc1 .Lscan_fwd_nopf
	v_add_u32_e32 v207, s12, v207
	v_add_u32_e32 v208, s12, v208
	v_add_u32_e32 v211, s12, v211
	ds_read_b128 v[78:81], v207 offset:16384
	ds_read_b128 v[82:85], v207 offset:40960
	ds_read_b128 v[86:89], v207 offset:24576
	ds_read_b128 v[90:93], v207 offset:32768
	ds_read_b128 v[94:97], v207 offset:0
	ds_read_b32 v98, v208 offset:8192
	ds_read_b32 v99, v211 offset:8192
.Lscan_fwd_nopf:
	v_pk_mul_f32 v[212:213], v[164:165], v[118:119] op_sel_hi:[1,0]
	v_pk_fma_f32 v[212:213], v[166:167], v[118:119], v[212:213] op_sel:[0,1,0] op_sel_hi:[1,1,1]
	v_add_f32_dpp v224, v217, v216 row_ror:8 row_mask:0xf bank_mask:0xf
	v_pk_fma_f32 v[212:213], v[168:169], v[120:121], v[212:213] op_sel_hi:[1,0,1]
	v_pk_fma_f32 v[212:213], v[170:171], v[120:121], v[212:213] op_sel:[0,1,0] op_sel_hi:[1,1,1]
	v_add_f32_dpp v224, v224, v224 quad_perm:[1,0,3,2] row_mask:0xf bank_mask:0xf
	v_pk_mul_f32 v[164:165], v[130:131], v[164:165] op_sel_hi:[0,1]
	v_pk_mul_f32 v[166:167], v[130:131], v[166:167] op_sel:[1,0] op_sel_hi:[1,1]
	v_add_f32_dpp v220, v213, v212 row_ror:8 row_mask:0xf bank_mask:0xf
	v_add_f32_dpp v224, v224, v224 quad_perm:[2,3,0,1] row_mask:0xf bank_mask:0xf
	v_pk_mul_f32 v[168:169], v[132:133], v[168:169] op_sel_hi:[0,1]
	v_add_f32_dpp v220, v220, v220 quad_perm:[1,0,3,2] row_mask:0xf bank_mask:0xf
	v_add_f32_dpp v224, v224, v224 row_half_mirror row_mask:0xf bank_mask:0xf
	v_pk_mul_f32 v[170:171], v[132:133], v[170:171] op_sel:[1,0] op_sel_hi:[1,1]
	v_pk_fma_f32 v[164:165], v[126:127], v[138:139], v[164:165] op_sel_hi:[0,1,1]
	v_add_f32_dpp v220, v220, v220 quad_perm:[2,3,0,1] row_mask:0xf bank_mask:0xf
	ds_write_b32 v209, v224 offset:49664
	v_pk_fma_f32 v[166:167], v[126:127], v[138:139], v[166:167] op_sel:[1,0,0] op_sel_hi:[1,1,1]
	v_pk_fma_f32 v[168:169], v[128:129], v[138:139], v[168:169] op_sel_hi:[0,1,1]
	v_add_f32_dpp v220, v220, v220 row_half_mirror row_mask:0xf bank_mask:0xf
	v_pk_fma_f32 v[170:171], v[128:129], v[138:139], v[170:171] op_sel:[1,0,0] op_sel_hi:[1,1,1]
	s_nop 0
	v_mov_b32_dpp v221, v220 row_ror:8 row_mask:0xf bank_mask:0xf
	v_pk_fma_f32 v[164:165], v[122:123], v[220:221], v[164:165] op_sel_hi:[0,1,1] neg_lo:[0,1,0] neg_hi:[0,1,0]
	v_pk_fma_f32 v[166:167], v[122:123], v[220:221], v[166:167] op_sel:[1,0,0] op_sel_hi:[1,1,1] neg_lo:[0,1,0] neg_hi:[0,1,0]
	v_pk_fma_f32 v[168:169], v[124:125], v[220:221], v[168:169] op_sel_hi:[0,1,1] neg_lo:[0,1,0] neg_hi:[0,1,0]
	v_pk_fma_f32 v[170:171], v[124:125], v[220:221], v[170:171] op_sel:[1,0,0] op_sel_hi:[1,1,1] neg_lo:[0,1,0] neg_hi:[0,1,0]
	v_pk_mul_f32 v[216:217], v[164:165], v[134:135] op_sel_hi:[1,0]
	v_pk_fma_f32 v[216:217], v[166:167], v[134:135], v[216:217] op_sel:[0,1,0] op_sel_hi:[1,1,1]
	v_pk_fma_f32 v[216:217], v[168:169], v[136:137], v[216:217] op_sel_hi:[1,0,1]
	v_pk_fma_f32 v[216:217], v[170:171], v[136:137], v[216:217] op_sel:[0,1,0] op_sel_hi:[1,1,1]
	s_add_i32 s11, s11, 1
	s_cmp_lg_u32 s11, 8
	s_cbranch_scc1 .Lscan_fwd_loop
	s_nop 1
	v_add_f32_dpp v224, v217, v216 row_ror:8 row_mask:0xf bank_mask:0xf
	s_nop 1
	v_add_f32_dpp v224, v224, v224 quad_perm:[1,0,3,2] row_mask:0xf bank_mask:0xf
	s_nop 1
	v_add_f32_dpp v224, v224, v224 quad_perm:[2,3,0,1] row_mask:0xf bank_mask:0xf
	s_nop 1
	v_add_f32_dpp v224, v224, v224 row_half_mirror row_mask:0xf bank_mask:0xf
	ds_write_b32 v209, v224 offset:49920
	s_branch .LBB0_691
.Lscan_rev:
	s_mov_b32 s12, 0xfffffc00
	v_add_u32_e32 v207, 0xfffffd00, v189
	v_add_u32_e32 v208, 0xfffffd00, v190
	v_add_u32_e32 v209, 0xfffffd00, v190
	v_add_u32_e32 v211, 0xfffffd00, v210
	s_waitcnt lgkmcnt(0)
	ds_read_b128 v[118:121], v207 offset:16896
	ds_read_b128 v[122:125], v207 offset:41472
	ds_read_b128 v[126:129], v207 offset:25088
	ds_read_b128 v[130:133], v207 offset:33280
	ds_read_b128 v[134:137], v207 offset:512
	ds_read_b32 v138, v208 offset:8704
	ds_read_b32 v139, v211 offset:8704
	v_pk_mul_f32 v[212:213], v[164:165], v[78:79] op_sel_hi:[1,0]
	v_pk_fma_f32 v[212:213], v[166:167], v[78:79], v[212:213] op_sel:[0,1,0] op_sel_hi:[1,1,1]
	v_pk_fma_f32 v[212:213], v[168:169], v[80:81], v[212:213] op_sel_hi:[1,0,1]
	v_pk_fma_f32 v[212:213], v[170:171], v[80:81], v[212:213] op_sel:[0,1,0] op_sel_hi:[1,1,1]
	v_pk_mul_f32 v[164:165], v[90:91], v[164:165] op_sel_hi:[0,1]
	v_pk_mul_f32 v[166:167], v[90:91], v[166:167] op_sel:[1,0] op_sel_hi:[1,1]
	v_add_f32_dpp v220, v213, v212 row_ror:8 row_mask:0xf bank_mask:0xf
	v_pk_mul_f32 v[168:169], v[92:93], v[168:169] op_sel_hi:[0,1]
	v_pk_mul_f32 v[170:171], v[92:93], v[170:171] op_sel:[1,0] op_sel_hi:[1,1]
	v_add_f32_dpp v220, v220, v220 quad_perm:[1,0,3,2] row_mask:0xf bank_mask:0xf
	v_pk_fma_f32 v[164:165], v[86:87], v[98:99], v[164:165] op_sel_hi:[0,1,1]
	v_pk_fma_f32 v[166:167], v[86:87], v[98:99], v[166:167] op_sel:[1,0,0] op_sel_hi:[1,1,1]
	v_add_f32_dpp v220, v220, v220 quad_perm:[2,3,0,1] row_mask:0xf bank_mask:0xf
	v_pk_fma_f32 v[168:169], v[88:89], v[98:99], v[168:169] op_sel_hi:[0,1,1]
	v_pk_fma_f32 v[170:171], v[88:89], v[98:99], v[170:171] op_sel:[1,0,0] op_sel_hi:[1,1,1]
	v_add_f32_dpp v220, v220, v220 row_half_mirror row_mask:0xf bank_mask:0xf
	s_nop 1
	v_mov_b32_dpp v221, v220 row_ror:8 row_mask:0xf bank_mask:0xf
	v_pk_fma_f32 v[164:165], v[82:83], v[220:221], v[164:165] op_sel_hi:[0,1,1] neg_lo:[0,1,0] neg_hi:[0,1,0]
	v_pk_fma_f32 v[166:167], v[82:83], v[220:221], v[166:167] op_sel:[1,0,0] op_sel_hi:[1,1,1] neg_lo:[0,1,0] neg_hi:[0,1,0]
	v_pk_fma_f32 v[168:169], v[84:85], v[220:221], v[168:169] op_sel_hi:[0,1,1] neg_lo:[0,1,0] neg_hi:[0,1,0]
	v_pk_fma_f32 v[170:171], v[84:85], v[220:221], v[170:171] op_sel:[1,0,0] op_sel_hi:[1,1,1] neg_lo:[0,1,0] neg_hi:[0,1,0]
	v_pk_mul_f32 v[216:217], v[164:165], v[94:95] op_sel_hi:[1,0]
	v_pk_fma_f32 v[216:217], v[166:167], v[94:95], v[216:217] op_sel:[0,1,0] op_sel_hi:[1,1,1]
	v_pk_fma_f32 v[216:217], v[168:169], v[96:97], v[216:217] op_sel_hi:[1,0,1]
	v_pk_fma_f32 v[216:217], v[170:171], v[96:97], v[216:217] op_sel:[0,1,0] op_sel_hi:[1,1,1]
	s_waitcnt lgkmcnt(0)
	ds_read_b128 v[78:81], v207 offset:16640
	ds_read_b128 v[82:85], v207 offset:41216
	ds_read_b128 v[86:89], v207 offset:24832
	ds_read_b128 v[90:93], v207 offset:33024
	ds_read_b128 v[94:97], v207 offset:256
	ds_read_b32 v98, v208 offset:8448
	ds_read_b32 v99, v211 offset:8448
	v_pk_mul_f32 v[212:213], v[164:165], v[118:119] op_sel_hi:[1,0]
	v_pk_fma_f32 v[212:213], v[166:167], v[118:119], v[212:213] op_sel:[0,1,0] op_sel_hi:[1,1,1]
	v_add_f32_dpp v224, v217, v216 row_ror:8 row_mask:0xf bank_mask:0xf
	v_pk_fma_f32 v[212:213], v[168:169], v[120:121], v[212:213] op_sel_hi:[1,0,1]
	v_pk_fma_f32 v[212:213], v[170:171], v[120:121], v[212:213] op_sel:[0,1,0] op_sel_hi:[1,1,1]
	v_add_f32_dpp v224, v224, v224 quad_perm:[1,0,3,2] row_mask:0xf bank_mask:0xf
	v_pk_mul_f32 v[164:165], v[130:131], v[164:165] op_sel_hi:[0,1]
	v_pk_mul_f32 v[166:167], v[130:131], v[166:167] op_sel:[1,0] op_sel_hi:[1,1]
	v_add_f32_dpp v220, v213, v212 row_ror:8 row_mask:0xf bank_mask:0xf
	v_add_f32_dpp v224, v224, v224 quad_perm:[2,3,0,1] row_mask:0xf bank_mask:0xf
	v_pk_mul_f32 v[168:169], v[132:133], v[168:169] op_sel_hi:[0,1]
	v_add_f32_dpp v220, v220, v220 quad_perm:[1,0,3,2] row_mask:0xf bank_mask:0xf
	v_add_f32_dpp v224, v224, v224 row_half_mirror row_mask:0xf bank_mask:0xf
	v_pk_mul_f32 v[170:171], v[132:133], v[170:171] op_sel:[1,0] op_sel_hi:[1,1]
	v_pk_fma_f32 v[164:165], v[126:127], v[138:139], v[164:165] op_sel_hi:[0,1,1]
	v_add_f32_dpp v220, v220, v220 quad_perm:[2,3,0,1] row_mask:0xf bank_mask:0xf
	ds_write_b32 v209, v224 offset:49920
	v_pk_fma_f32 v[166:167], v[126:127], v[138:139], v[166:167] op_sel:[1,0,0] op_sel_hi:[1,1,1]
	v_pk_fma_f32 v[168:169], v[128:129], v[138:139], v[168:169] op_sel_hi:[0,1,1]
	v_add_f32_dpp v220, v220, v220 row_half_mirror row_mask:0xf bank_mask:0xf
	v_pk_fma_f32 v[170:171], v[128:129], v[138:139], v[170:171] op_sel:[1,0,0] op_sel_hi:[1,1,1]
	s_nop 0
	v_mov_b32_dpp v221, v220 row_ror:8 row_mask:0xf bank_mask:0xf
	v_pk_fma_f32 v[164:165], v[122:123], v[220:221], v[164:165] op_sel_hi:[0,1,1] neg_lo:[0,1,0] neg_hi:[0,1,0]
	v_pk_fma_f32 v[166:167], v[122:123], v[220:221], v[166:167] op_sel:[1,0,0] op_sel_hi:[1,1,1] neg_lo:[0,1,0] neg_hi:[0,1,0]
	v_pk_fma_f32 v[168:169], v[124:125], v[220:221], v[168:169] op_sel_hi:[0,1,1] neg_lo:[0,1,0] neg_hi:[0,1,0]
	v_pk_fma_f32 v[170:171], v[124:125], v[220:221], v[170:171] op_sel:[1,0,0] op_sel_hi:[1,1,1] neg_lo:[0,1,0] neg_hi:[0,1,0]
	v_pk_mul_f32 v[216:217], v[164:165], v[134:135] op_sel_hi:[1,0]
	v_pk_fma_f32 v[216:217], v[166:167], v[134:135], v[216:217] op_sel:[0,1,0] op_sel_hi:[1,1,1]
	v_pk_fma_f32 v[216:217], v[168:169], v[136:137], v[216:217] op_sel_hi:[1,0,1]
	v_pk_fma_f32 v[216:217], v[170:171], v[136:137], v[216:217] op_sel:[0,1,0] op_sel_hi:[1,1,1]
	s_waitcnt lgkmcnt(0)
	ds_read_b128 v[118:121], v207 offset:16384
	ds_read_b128 v[122:125], v207 offset:40960
	ds_read_b128 v[126:129], v207 offset:24576
	ds_read_b128 v[130:133], v207 offset:32768
	ds_read_b128 v[134:137], v207 offset:0
	ds_read_b32 v138, v208 offset:8192
	ds_read_b32 v139, v211 offset:8192
	v_pk_mul_f32 v[212:213], v[164:165], v[78:79] op_sel_hi:[1,0]
	v_pk_fma_f32 v[212:213], v[166:167], v[78:79], v[212:213] op_sel:[0,1,0] op_sel_hi:[1,1,1]
	v_add_f32_dpp v224, v217, v216 row_ror:8 row_mask:0xf bank_mask:0xf
	v_pk_fma_f32 v[212:213], v[168:169], v[80:81], v[212:213] op_sel_hi:[1,0,1]
	v_pk_fma_f32 v[212:213], v[170:171], v[80:81], v[212:213] op_sel:[0,1,0] op_sel_hi:[1,1,1]
	v_add_f32_dpp v224, v224, v224 quad_perm:[1,0,3,2] row_mask:0xf bank_mask:0xf
	v_pk_mul_f32 v[164:165], v[90:91], v[164:165] op_sel_hi:[0,1]
	v_pk_mul_f32 v[166:167], v[90:91], v[166:167] op_sel:[1,0] op_sel_hi:[1,1]
	v_add_f32_dpp v220, v213, v212 row_ror:8 row_mask:0xf bank_mask:0xf
	v_add_f32_dpp v224, v224, v224 quad_perm:[2,3,0,1] row_mask:0xf bank_mask:0xf
	v_pk_mul_f32 v[168:169], v[92:93], v[168:169] op_sel_hi:[0,1]
	v_add_f32_dpp v220, v220, v220 quad_perm:[1,0,3,2] row_mask:0xf bank_mask:0xf
	v_add_f32_dpp v224, v224, v224 row_half_mirror row_mask:0xf bank_mask:0xf
	v_pk_mul_f32 v[170:171], v[92:93], v[170:171] op_sel:[1,0] op_sel_hi:[1,1]
	v_pk_fma_f32 v[164:165], v[86:87], v[98:99], v[164:165] op_sel_hi:[0,1,1]
	v_add_f32_dpp v220, v220, v220 quad_perm:[2,3,0,1] row_mask:0xf bank_mask:0xf
	ds_write_b32 v209, v224 offset:49664
	v_pk_fma_f32 v[166:167], v[86:87], v[98:99], v[166:167] op_sel:[1,0,0] op_sel_hi:[1,1,1]
	v_pk_fma_f32 v[168:169], v[88:89], v[98:99], v[168:169] op_sel_hi:[0,1,1]
	v_add_f32_dpp v220, v220, v220 row_half_mirror row_mask:0xf bank_mask:0xf
	v_pk_fma_f32 v[170:171], v[88:89], v[98:99], v[170:171] op_sel:[1,0,0] op_sel_hi:[1,1,1]
	s_nop 0
	v_mov_b32_dpp v221, v220 row_ror:8 row_mask:0xf bank_mask:0xf
	v_pk_fma_f32 v[164:165], v[82:83], v[220:221], v[164:165] op_sel_hi:[0,1,1] neg_lo:[0,1,0] neg_hi:[0,1,0]
	v_pk_fma_f32 v[166:167], v[82:83], v[220:221], v[166:167] op_sel:[1,0,0] op_sel_hi:[1,1,1] neg_lo:[0,1,0] neg_hi:[0,1,0]
	v_pk_fma_f32 v[168:169], v[84:85], v[220:221], v[168:169] op_sel_hi:[0,1,1] neg_lo:[0,1,0] neg_hi:[0,1,0]
	v_pk_fma_f32 v[170:171], v[84:85], v[220:221], v[170:171] op_sel:[1,0,0] op_sel_hi:[1,1,1] neg_lo:[0,1,0] neg_hi:[0,1,0]
	v_pk_mul_f32 v[216:217], v[164:165], v[94:95] op_sel_hi:[1,0]
	v_pk_fma_f32 v[216:217], v[166:167], v[94:95], v[216:217] op_sel:[0,1,0] op_sel_hi:[1,1,1]
	v_pk_fma_f32 v[216:217], v[168:169], v[96:97], v[216:217] op_sel_hi:[1,0,1]
	v_pk_fma_f32 v[216:217], v[170:171], v[96:97], v[216:217] op_sel:[0,1,0] op_sel_hi:[1,1,1]
	s_waitcnt lgkmcnt(0)
	v_add_u32_e32 v207, s12, v207
	v_add_u32_e32 v208, s12, v208
	v_add_u32_e32 v211, s12, v211
	ds_read_b128 v[78:81], v207 offset:17152
	ds_read_b128 v[82:85], v207 offset:41728
	ds_read_b128 v[86:89], v207 offset:25344
	ds_read_b128 v[90:93], v207 offset:33536
	ds_read_b128 v[94:97], v207 offset:768
	ds_read_b32 v98, v208 offset:8960
	ds_read_b32 v99, v211 offset:8960
	v_pk_mul_f32 v[212:213], v[164:165], v[118:119] op_sel_hi:[1,0]
	v_pk_fma_f32 v[212:213], v[166:167], v[118:119], v[212:213] op_sel:[0,1,0] op_sel_hi:[1,1,1]
	v_add_f32_dpp v224, v217, v216 row_ror:8 row_mask:0xf bank_mask:0xf
	v_pk_fma_f32 v[212:213], v[168:169], v[120:121], v[212:213] op_sel_hi:[1,0,1]
	v_pk_fma_f32 v[212:213], v[170:171], v[120:121], v[212:213] op_sel:[0,1,0] op_sel_hi:[1,1,1]
	v_add_f32_dpp v224, v224, v224 quad_perm:[1,0,3,2] row_mask:0xf bank_mask:0xf
	v_pk_mul_f32 v[164:165], v[130:131], v[164:165] op_sel_hi:[0,1]
	v_pk_mul_f32 v[166:167], v[130:131], v[166:167] op_sel:[1,0] op_sel_hi:[1,1]
	v_add_f32_dpp v220, v213, v212 row_ror:8 row_mask:0xf bank_mask:0xf
	v_add_f32_dpp v224, v224, v224 quad_perm:[2,3,0,1] row_mask:0xf bank_mask:0xf
	v_pk_mul_f32 v[168:169], v[132:133], v[168:169] op_sel_hi:[0,1]
	v_add_f32_dpp v220, v220, v220 quad_perm:[1,0,3,2] row_mask:0xf bank_mask:0xf
	v_add_f32_dpp v224, v224, v224 row_half_mirror row_mask:0xf bank_mask:0xf
	v_pk_mul_f32 v[170:171], v[132:133], v[170:171] op_sel:[1,0] op_sel_hi:[1,1]
	v_pk_fma_f32 v[164:165], v[126:127], v[138:139], v[164:165] op_sel_hi:[0,1,1]
	v_add_f32_dpp v220, v220, v220 quad_perm:[2,3,0,1] row_mask:0xf bank_mask:0xf
	ds_write_b32 v209, v224 offset:49408
	v_pk_fma_f32 v[166:167], v[126:127], v[138:139], v[166:167] op_sel:[1,0,0] op_sel_hi:[1,1,1]
	v_pk_fma_f32 v[168:169], v[128:129], v[138:139], v[168:169] op_sel_hi:[0,1,1]
	v_add_f32_dpp v220, v220, v220 row_half_mirror row_mask:0xf bank_mask:0xf
	v_pk_fma_f32 v[170:171], v[128:129], v[138:139], v[170:171] op_sel:[1,0,0] op_sel_hi:[1,1,1]
	s_nop 0
	v_mov_b32_dpp v221, v220 row_ror:8 row_mask:0xf bank_mask:0xf
	v_pk_fma_f32 v[164:165], v[122:123], v[220:221], v[164:165] op_sel_hi:[0,1,1] neg_lo:[0,1,0] neg_hi:[0,1,0]
	v_pk_fma_f32 v[166:167], v[122:123], v[220:221], v[166:167] op_sel:[1,0,0] op_sel_hi:[1,1,1] neg_lo:[0,1,0] neg_hi:[0,1,0]
	v_pk_fma_f32 v[168:169], v[124:125], v[220:221], v[168:169] op_sel_hi:[0,1,1] neg_lo:[0,1,0] neg_hi:[0,1,0]
	v_pk_fma_f32 v[170:171], v[124:125], v[220:221], v[170:171] op_sel:[1,0,0] op_sel_hi:[1,1,1] neg_lo:[0,1,0] neg_hi:[0,1,0]
	v_pk_mul_f32 v[216:217], v[164:165], v[134:135] op_sel_hi:[1,0]
	v_pk_fma_f32 v[216:217], v[166:167], v[134:135], v[216:217] op_sel:[0,1,0] op_sel_hi:[1,1,1]
	v_pk_fma_f32 v[216:217], v[168:169], v[136:137], v[216:217] op_sel_hi:[1,0,1]
	v_pk_fma_f32 v[216:217], v[170:171], v[136:137], v[216:217] op_sel:[0,1,0] op_sel_hi:[1,1,1]
	s_mov_b32 s11, 1
.Lscan_rev_loop:
	s_waitcnt lgkmcnt(0)
	ds_read_b128 v[118:121], v207 offset:16896
	ds_read_b128 v[122:125], v207 offset:41472
	ds_read_b128 v[126:129], v207 offset:25088
	ds_read_b128 v[130:133], v207 offset:33280
	ds_read_b128 v[134:137], v207 offset:512
	ds_read_b32 v138, v208 offset:8704
	ds_read_b32 v139, v211 offset:8704
	v_pk_mul_f32 v[212:213], v[164:165], v[78:79] op_sel_hi:[1,0]
	v_pk_fma_f32 v[212:213], v[166:167], v[78:79], v[212:213] op_sel:[0,1,0] op_sel_hi:[1,1,1]
	v_add_f32_dpp v224, v217, v216 row_ror:8 row_mask:0xf bank_mask:0xf
	v_pk_fma_f32 v[212:213], v[168:169], v[80:81], v[212:213] op_sel_hi:[1,0,1]
	v_pk_fma_f32 v[212:213], v[170:171], v[80:81], v[212:213] op_sel:[0,1,0] op_sel_hi:[1,1,1]
	v_add_f32_dpp v224, v224, v224 quad_perm:[1,0,3,2] row_mask:0xf bank_mask:0xf
	v_pk_mul_f32 v[164:165], v[90:91], v[164:165] op_sel_hi:[0,1]
	v_pk_mul_f32 v[166:167], v[90:91], v[166:167] op_sel:[1,0] op_sel_hi:[1,1]
	v_add_f32_dpp v220, v213, v212 row_ror:8 row_mask:0xf bank_mask:0xf
	v_add_f32_dpp v224, v224, v224 quad_perm:[2,3,0,1] row_mask:0xf bank_mask:0xf
	v_pk_mul_f32 v[168:169], v[92:93], v[168:169] op_sel_hi:[0,1]
	v_add_f32_dpp v220, v220, v220 quad_perm:[1,0,3,2] row_mask:0xf bank_mask:0xf
	v_add_f32_dpp v224, v224, v224 row_half_mirror row_mask:0xf bank_mask:0xf
	v_pk_mul_f32 v[170:171], v[92:93], v[170:171] op_sel:[1,0] op_sel_hi:[1,1]
	v_pk_fma_f32 v[164:165], v[86:87], v[98:99], v[164:165] op_sel_hi:[0,1,1]
	v_add_f32_dpp v220, v220, v220 quad_perm:[2,3,0,1] row_mask:0xf bank_mask:0xf
	ds_write_b32 v209, v224 offset:49152
	v_add_u32_e32 v209, s12, v209
	v_pk_fma_f32 v[166:167], v[86:87], v[98:99], v[166:167] op_sel:[1,0,0] op_sel_hi:[1,1,1]
	v_pk_fma_f32 v[168:169], v[88:89], v[98:99], v[168:169] op_sel_hi:[0,1,1]
	v_add_f32_dpp v220, v220, v220 row_half_mirror row_mask:0xf bank_mask:0xf
	v_pk_fma_f32 v[170:171], v[88:89], v[98:99], v[170:171] op_sel:[1,0,0] op_sel_hi:[1,1,1]
	s_nop 0
	v_mov_b32_dpp v221, v220 row_ror:8 row_mask:0xf bank_mask:0xf
	v_pk_fma_f32 v[164:165], v[82:83], v[220:221], v[164:165] op_sel_hi:[0,1,1] neg_lo:[0,1,0] neg_hi:[0,1,0]
	v_pk_fma_f32 v[166:167], v[82:83], v[220:221], v[166:167] op_sel:[1,0,0] op_sel_hi:[1,1,1] neg_lo:[0,1,0] neg_hi:[0,1,0]
	v_pk_fma_f32 v[168:169], v[84:85], v[220:221], v[168:169] op_sel_hi:[0,1,1] neg_lo:[0,1,0] neg_hi:[0,1,0]
	v_pk_fma_f32 v[170:171], v[84:85], v[220:221], v[170:171] op_sel:[1,0,0] op_sel_hi:[1,1,1] neg_lo:[0,1,0] neg_hi:[0,1,0]
	v_pk_mul_f32 v[216:217], v[164:165], v[94:95] op_sel_hi:[1,0]
	v_pk_fma_f32 v[216:217], v[166:167], v[94:95], v[216:217] op_sel:[0,1,0] op_sel_hi:[1,1,1]
	v_pk_fma_f32 v[216:217], v[168:169], v[96:97], v[216:217] op_sel_hi:[1,0,1]
	v_pk_fma_f32 v[216:217], v[170:171], v[96:97], v[216:217] op_sel:[0,1,0] op_sel_hi:[1,1,1]
	s_waitcnt lgkmcnt(0)
	ds_read_b128 v[78:81], v207 offset:16640
	ds_read_b128 v[82:85], v207 offset:41216
	ds_read_b128 v[86:89], v207 offset:24832
	ds_read_b128 v[90:93], v207 offset:33024
	ds_read_b128 v[94:97], v207 offset:256
	ds_read_b32 v98, v208 offset:8448
	ds_read_b32 v99, v211 offset:8448
	v_pk_mul_f32 v[212:213], v[164:165], v[118:119] op_sel_hi:[1,0]
	v_pk_fma_f32 v[212:213], v[166:167], v[118:119], v[212:213] op_sel:[0,1,0] op_sel_hi:[1,1,1]
	v_add_f32_dpp v224, v217, v216 row_ror:8 row_mask:0xf bank_mask:0xf
	v_pk_fma_f32 v[212:213], v[168:169], v[120:121], v[212:213] op_sel_hi:[1,0,1]
	v_pk_fma_f32 v[212:213], v[170:171], v[120:121], v[212:213] op_sel:[0,1,0] op_sel_hi:[1,1,1]
	v_add_f32_dpp v224, v224, v224 quad_perm:[1,0,3,2] row_mask:0xf bank_mask:0xf
	v_pk_mul_f32 v[164:165], v[130:131], v[164:165] op_sel_hi:[0,1]
	v_pk_mul_f32 v[166:167], v[130:131], v[166:167] op_sel:[1,0] op_sel_hi:[1,1]
	v_add_f32_dpp v220, v213, v212 row_ror:8 row_mask:0xf bank_mask:0xf
	v_add_f32_dpp v224, v224, v224 quad_perm:[2,3,0,1] row_mask:0xf bank_mask:0xf
	v_pk_mul_f32 v[168:169], v[132:133], v[168:169] op_sel_hi:[0,1]
	v_add_f32_dpp v220, v220, v220 quad_perm:[1,0,3,2] row_mask:0xf bank_mask:0xf
	v_add_f32_dpp v224, v224, v224 row_half_mirror row_mask:0xf bank_mask:0xf
	v_pk_mul_f32 v[170:171], v[132:133], v[170:171] op_sel:[1,0] op_sel_hi:[1,1]
	v_pk_fma_f32 v[164:165], v[126:127], v[138:139], v[164:165] op_sel_hi:[0,1,1]
	v_add_f32_dpp v220, v220, v220 quad_perm:[2,3,0,1] row_mask:0xf bank_mask:0xf
	ds_write_b32 v209, v224 offset:49920
	v_pk_fma_f32 v[166:167], v[126:127], v[138:139], v[166:167] op_sel:[1,0,0] op_sel_hi:[1,1,1]
	v_pk_fma_f32 v[168:169], v[128:129], v[138:139], v[168:169] op_sel_hi:[0,1,1]
	v_add_f32_dpp v220, v220, v220 row_half_mirror row_mask:0xf bank_mask:0xf
	v_pk_fma_f32 v[170:171], v[128:129], v[138:139], v[170:171] op_sel:[1,0,0] op_sel_hi:[1,1,1]
	s_nop 0
	v_mov_b32_dpp v221, v220 row_ror:8 row_mask:0xf bank_mask:0xf
	v_pk_fma_f32 v[164:165], v[122:123], v[220:221], v[164:165] op_sel_hi:[0,1,1] neg_lo:[0,1,0] neg_hi:[0,1,0]
	v_pk_fma_f32 v[166:167], v[122:123], v[220:221], v[166:167] op_sel:[1,0,0] op_sel_hi:[1,1,1] neg_lo:[0,1,0] neg_hi:[0,1,0]
	v_pk_fma_f32 v[168:169], v[124:125], v[220:221], v[168:169] op_sel_hi:[0,1,1] neg_lo:[0,1,0] neg_hi:[0,1,0]
	v_pk_fma_f32 v[170:171], v[124:125], v[220:221], v[170:171] op_sel:[1,0,0] op_sel_hi:[1,1,1] neg_lo:[0,1,0] neg_hi:[0,1,0]
	v_pk_mul_f32 v[216:217], v[164:165], v[134:135] op_sel_hi:[1,0]
	v_pk_fma_f32 v[216:217], v[166:167], v[134:135], v[216:217] op_sel:[0,1,0] op_sel_hi:[1,1,1]
	v_pk_fma_f32 v[216:217], v[168:169], v[136:137], v[216:217] op_sel_hi:[1,0,1]
	v_pk_fma_f32 v[216:217], v[170:171], v[136:137], v[216:217] op_sel:[0,1,0] op_sel_hi:[1,1,1]
	s_waitcnt lgkmcnt(0)
	ds_read_b128 v[118:121], v207 offset:16384
	ds_read_b128 v[122:125], v207 offset:40960
	ds_read_b128 v[126:129], v207 offset:24576
	ds_read_b128 v[130:133], v207 offset:32768
	ds_read_b128 v[134:137], v207 offset:0
	ds_read_b32 v138, v208 offset:8192
	ds_read_b32 v139, v211 offset:8192
	v_pk_mul_f32 v[212:213], v[164:165], v[78:79] op_sel_hi:[1,0]
	v_pk_fma_f32 v[212:213], v[166:167], v[78:79], v[212:213] op_sel:[0,1,0] op_sel_hi:[1,1,1]
	v_add_f32_dpp v224, v217, v216 row_ror:8 row_mask:0xf bank_mask:0xf
	v_pk_fma_f32 v[212:213], v[168:169], v[80:81], v[212:213] op_sel_hi:[1,0,1]
	v_pk_fma_f32 v[212:213], v[170:171], v[80:81], v[212:213] op_sel:[0,1,0] op_sel_hi:[1,1,1]
	v_add_f32_dpp v224, v224, v224 quad_perm:[1,0,3,2] row_mask:0xf bank_mask:0xf
	v_pk_mul_f32 v[164:165], v[90:91], v[164:165] op_sel_hi:[0,1]
	v_pk_mul_f32 v[166:167], v[90:91], v[166:167] op_sel:[1,0] op_sel_hi:[1,1]
	v_add_f32_dpp v220, v213, v212 row_ror:8 row_mask:0xf bank_mask:0xf
	v_add_f32_dpp v224, v224, v224 quad_perm:[2,3,0,1] row_mask:0xf bank_mask:0xf
	v_pk_mul_f32 v[168:169], v[92:93], v[168:169] op_sel_hi:[0,1]
	v_add_f32_dpp v220, v220, v220 quad_perm:[1,0,3,2] row_mask:0xf bank_mask:0xf
	v_add_f32_dpp v224, v224, v224 row_half_mirror row_mask:0xf bank_mask:0xf
	v_pk_mul_f32 v[170:171], v[92:93], v[170:171] op_sel:[1,0] op_sel_hi:[1,1]
	v_pk_fma_f32 v[164:165], v[86:87], v[98:99], v[164:165] op_sel_hi:[0,1,1]
	v_add_f32_dpp v220, v220, v220 quad_perm:[2,3,0,1] row_mask:0xf bank_mask:0xf
	ds_write_b32 v209, v224 offset:49664
	v_pk_fma_f32 v[166:167], v[86:87], v[98:99], v[166:167] op_sel:[1,0,0] op_sel_hi:[1,1,1]
	v_pk_fma_f32 v[168:169], v[88:89], v[98:99], v[168:169] op_sel_hi:[0,1,1]
	v_add_f32_dpp v220, v220, v220 row_half_mirror row_mask:0xf bank_mask:0xf
	v_pk_fma_f32 v[170:171], v[88:89], v[98:99], v[170:171] op_sel:[1,0,0] op_sel_hi:[1,1,1]
	s_nop 0
	v_mov_b32_dpp v221, v220 row_ror:8 row_mask:0xf bank_mask:0xf
	v_pk_fma_f32 v[164:165], v[82:83], v[220:221], v[164:165] op_sel_hi:[0,1,1] neg_lo:[0,1,0] neg_hi:[0,1,0]
	v_pk_fma_f32 v[166:167], v[82:83], v[220:221], v[166:167] op_sel:[1,0,0] op_sel_hi:[1,1,1] neg_lo:[0,1,0] neg_hi:[0,1,0]
	v_pk_fma_f32 v[168:169], v[84:85], v[220:221], v[168:169] op_sel_hi:[0,1,1] neg_lo:[0,1,0] neg_hi:[0,1,0]
	v_pk_fma_f32 v[170:171], v[84:85], v[220:221], v[170:171] op_sel:[1,0,0] op_sel_hi:[1,1,1] neg_lo:[0,1,0] neg_hi:[0,1,0]
	v_pk_mul_f32 v[216:217], v[164:165], v[94:95] op_sel_hi:[1,0]
	v_pk_fma_f32 v[216:217], v[166:167], v[94:95], v[216:217] op_sel:[0,1,0] op_sel_hi:[1,1,1]
	v_pk_fma_f32 v[216:217], v[168:169], v[96:97], v[216:217] op_sel_hi:[1,0,1]
	v_pk_fma_f32 v[216:217], v[170:171], v[96:97], v[216:217] op_sel:[0,1,0] op_sel_hi:[1,1,1]
	s_waitcnt lgkmcnt(0)
	s_cmp_eq_u32 s11, 7
	s_cbranch_scc1 .Lscan_rev_nopf
	v_add_u32_e32 v207, s12, v207
	v_add_u32_e32 v208, s12, v208
	v_add_u32_e32 v211, s12, v211
	ds_read_b128 v[78:81], v207 offset:17152
	ds_read_b128 v[82:85], v207 offset:41728
	ds_read_b128 v[86:89], v207 offset:25344
	ds_read_b128 v[90:93], v207 offset:33536
	ds_read_b128 v[94:97], v207 offset:768
	ds_read_b32 v98, v208 offset:8960
	ds_read_b32 v99, v211 offset:8960
.Lscan_rev_nopf:
	v_pk_mul_f32 v[212:213], v[164:165], v[118:119] op_sel_hi:[1,0]
	v_pk_fma_f32 v[212:213], v[166:167], v[118:119], v[212:213] op_sel:[0,1,0] op_sel_hi:[1,1,1]
	v_add_f32_dpp v224, v217, v216 row_ror:8 row_mask:0xf bank_mask:0xf
	v_pk_fma_f32 v[212:213], v[168:169], v[120:121], v[212:213] op_sel_hi:[1,0,1]
	v_pk_fma_f32 v[212:213], v[170:171], v[120:121], v[212:213] op_sel:[0,1,0] op_sel_hi:[1,1,1]
	v_add_f32_dpp v224, v224, v224 quad_perm:[1,0,3,2] row_mask:0xf bank_mask:0xf
	v_pk_mul_f32 v[164:165], v[130:131], v[164:165] op_sel_hi:[0,1]
	v_pk_mul_f32 v[166:167], v[130:131], v[166:167] op_sel:[1,0] op_sel_hi:[1,1]
	v_add_f32_dpp v220, v213, v212 row_ror:8 row_mask:0xf bank_mask:0xf
	v_add_f32_dpp v224, v224, v224 quad_perm:[2,3,0,1] row_mask:0xf bank_mask:0xf
	v_pk_mul_f32 v[168:169], v[132:133], v[168:169] op_sel_hi:[0,1]
	v_add_f32_dpp v220, v220, v220 quad_perm:[1,0,3,2] row_mask:0xf bank_mask:0xf
	v_add_f32_dpp v224, v224, v224 row_half_mirror row_mask:0xf bank_mask:0xf
	v_pk_mul_f32 v[170:171], v[132:133], v[170:171] op_sel:[1,0] op_sel_hi:[1,1]
	v_pk_fma_f32 v[164:165], v[126:127], v[138:139], v[164:165] op_sel_hi:[0,1,1]
	v_add_f32_dpp v220, v220, v220 quad_perm:[2,3,0,1] row_mask:0xf bank_mask:0xf
	ds_write_b32 v209, v224 offset:49408
	v_pk_fma_f32 v[166:167], v[126:127], v[138:139], v[166:167] op_sel:[1,0,0] op_sel_hi:[1,1,1]
	v_pk_fma_f32 v[168:169], v[128:129], v[138:139], v[168:169] op_sel_hi:[0,1,1]
	v_add_f32_dpp v220, v220, v220 row_half_mirror row_mask:0xf bank_mask:0xf
	v_pk_fma_f32 v[170:171], v[128:129], v[138:139], v[170:171] op_sel:[1,0,0] op_sel_hi:[1,1,1]
	s_nop 0
	v_mov_b32_dpp v221, v220 row_ror:8 row_mask:0xf bank_mask:0xf
	v_pk_fma_f32 v[164:165], v[122:123], v[220:221], v[164:165] op_sel_hi:[0,1,1] neg_lo:[0,1,0] neg_hi:[0,1,0]
	v_pk_fma_f32 v[166:167], v[122:123], v[220:221], v[166:167] op_sel:[1,0,0] op_sel_hi:[1,1,1] neg_lo:[0,1,0] neg_hi:[0,1,0]
	v_pk_fma_f32 v[168:169], v[124:125], v[220:221], v[168:169] op_sel_hi:[0,1,1] neg_lo:[0,1,0] neg_hi:[0,1,0]
	v_pk_fma_f32 v[170:171], v[124:125], v[220:221], v[170:171] op_sel:[1,0,0] op_sel_hi:[1,1,1] neg_lo:[0,1,0] neg_hi:[0,1,0]
	v_pk_mul_f32 v[216:217], v[164:165], v[134:135] op_sel_hi:[1,0]
	v_pk_fma_f32 v[216:217], v[166:167], v[134:135], v[216:217] op_sel:[0,1,0] op_sel_hi:[1,1,1]
	v_pk_fma_f32 v[216:217], v[168:169], v[136:137], v[216:217] op_sel_hi:[1,0,1]
	v_pk_fma_f32 v[216:217], v[170:171], v[136:137], v[216:217] op_sel:[0,1,0] op_sel_hi:[1,1,1]
	s_add_i32 s11, s11, 1
	s_cmp_lg_u32 s11, 8
	s_cbranch_scc1 .Lscan_rev_loop
	s_nop 1
	v_add_f32_dpp v224, v217, v216 row_ror:8 row_mask:0xf bank_mask:0xf
	s_nop 1
	v_add_f32_dpp v224, v224, v224 quad_perm:[1,0,3,2] row_mask:0xf bank_mask:0xf
	s_nop 1
	v_add_f32_dpp v224, v224, v224 quad_perm:[2,3,0,1] row_mask:0xf bank_mask:0xf
	s_nop 1
	v_add_f32_dpp v224, v224, v224 row_half_mirror row_mask:0xf bank_mask:0xf
	ds_write_b32 v209, v224 offset:49152
